# GEMM main loops: the back-to-back s_setprio 0 / s_setprio 1 pairs between the two 16-MFMA blocks of a super-phase removed (priority stays raised across both blocks); 12 sites
# baseline (speedup 1.0000x reference)
; #define PG8_STAGE(bufoff, gbase, voff) do { _Pragma("unroll") for (int _i = 0; _i < 2; ++_i) \
;         __builtin_amdgcn_global_load_lds((const unsigned*)((const char*)(gbase) + (voff)[_i]), (PG8_LAS unsigned*)(lds + (bufoff) + ldsw + _i * 8192), 16, 0, 0); } while (0)
; #define PG8_LDA(dst, b, h) do { _Pragma("unroll") for (int m = 0; m < 4; ++m) _Pragma("unroll") for (int k = 0; k < 2; ++k) dst[m][k] = *(const PG8_LAS bf16x8*)(lds + PG8_SA(b, h) + aoff + m * 2048 + k * 1024); } while (0)
; #define PG8_LDB(dst, b, h) do { _Pragma("unroll") for (int n = 0; n < 2; ++n) _Pragma("unroll") for (int k = 0; k < 2; ++k) dst[n][k] = *(const PG8_LAS bf16x8*)(lds + PG8_SB(b, h) + boff + n * 2048 + k * 1024); } while (0)
; #define PG8_MMA(ai, bj, At, Bt) do { __builtin_amdgcn_s_setprio(1); _Pragma("unroll") for (int m = 0; m < 4; ++m) _Pragma("unroll") for (int n = 0; n < 2; ++n) _Pragma("unroll") for (int k = 0; k < 2; ++k) \
;         acc[ai][bj][m][n] = __builtin_amdgcn_mfma_f32_16x16x32_bf16(Bt[n][k], At[m][k], acc[ai][bj][m][n], 0, 0, 0); __builtin_amdgcn_s_setprio(0); } while (0)
; #define PG8_WAIT_V(n) asm volatile("s_waitcnt vmcnt(" #n ")" ::: "memory")
; #define PG8_WAIT_L(n) asm volatile("s_waitcnt lgkmcnt(" #n ")" ::: "memory")
; #define PG8_BAR __builtin_amdgcn_s_barrier()
; #define PG8_SCHED __builtin_amdgcn_sched_barrier(0)
; template <class Epi, class Sched, bool ALIGN_EPI = false, bool SP2 = false>
; __device__ __forceinline__ void gemm_phase(PG8_LAS unsigned char* lds, const Gemm g, const Sched& S, const Epi& E) {
;     ...
;             PG8_LDB(B0, 0, 0); PG8_LDB(B1, 0, 1); PG8_SCHED; PG8_LDA(At, 0, 0); PG8_STAGE(PG8_SA(1, 1), a1 + hstep, voffA);
;             PG8_WAIT_V(8); PG8_WAIT_L(0); PG8_BAR; PG8_MMA(0, 0, At, B0); PG8_MMA(0, 1, At, B1); PG8_BAR; PG8_SCHED;
;             PG8_LDA(At, 0, 1); PG8_STAGE(PG8_SB(0, 0), b2, voffB); PG8_STAGE(PG8_SB(0, 1), b2 + hstep, voffB); PG8_STAGE(PG8_SA(0, 0), a2, voffA);
;             PG8_WAIT_V(8); PG8_WAIT_L(0); PG8_BAR; PG8_MMA(1, 0, At, B0); PG8_MMA(1, 1, At, B1); PG8_BAR; PG8_SCHED;
.LBB0_161:
	s_add_u32 s8, s6, 0xfff80080
	s_addc_u32 s9, s7, -1
	s_add_i32 s93, 0, 0x10000
	s_cmp_eq_u32 s85, 28
	s_cselect_b32 s11, s15, s9
	s_cselect_b32 s10, s29, s8
	v_add_u32_e32 v151, s93, v135
	s_cselect_b32 s9, s45, s84
	s_cselect_b32 s8, s60, s73
	s_add_i32 s97, 0, 0x14000
	ds_read_b128 v[152:155], v151
	ds_read_b128 v[156:159], v151 offset:1024
	ds_read_b128 v[160:163], v151 offset:2048
	ds_read_b128 v[164:167], v151 offset:3072
	v_add_u32_e32 v151, s97, v135
	ds_read_b128 v[168:171], v151
	ds_read_b128 v[172:175], v151 offset:1024
	ds_read_b128 v[180:183], v151 offset:2048
	ds_read_b128 v[184:187], v151 offset:3072
	v_lshl_add_u64 v[196:197], s[6:7], 0, v[146:147]
	s_add_i32 m0, s90, 0xc000
	ds_read_b128 v[188:191], v178
	ds_read_b128 v[192:195], v178 offset:1024
	ds_read_b128 v[200:203], v178 offset:2048
	ds_read_b128 v[204:207], v178 offset:3072
	ds_read_b128 v[208:211], v178 offset:4096
	ds_read_b128 v[212:215], v178 offset:5120
	ds_read_b128 v[216:219], v178 offset:6144
	ds_read_b128 v[236:239], v178 offset:7168
	global_load_lds_dwordx4 v[196:197], off
	v_lshl_add_u64 v[196:197], s[6:7], 0, v[148:149]
	s_add_i32 m0, s90, 0xe000
	s_nop 0
	global_load_lds_dwordx4 v[196:197], off
	s_waitcnt vmcnt(8)
	s_waitcnt lgkmcnt(0)
	s_barrier
	s_setprio 1
	v_mfma_f32_16x16x32_bf16 v[130:133], v[152:155], v[188:191], v[130:133]
	v_mfma_f32_16x16x32_bf16 v[126:129], v[160:163], v[188:191], v[126:129]
	v_mfma_f32_16x16x32_bf16 v[114:117], v[152:155], v[200:203], v[114:117]
	v_mfma_f32_16x16x32_bf16 v[110:113], v[160:163], v[200:203], v[110:113]
	v_mfma_f32_16x16x32_bf16 v[98:101], v[152:155], v[208:211], v[98:101]
	v_mfma_f32_16x16x32_bf16 v[94:97], v[160:163], v[208:211], v[94:97]
	v_mfma_f32_16x16x32_bf16 v[82:85], v[152:155], v[216:219], v[82:85]
	v_mfma_f32_16x16x32_bf16 v[78:81], v[160:163], v[216:219], v[78:81]
	v_mfma_f32_16x16x32_bf16 v[130:133], v[156:159], v[192:195], v[130:133]
	v_mfma_f32_16x16x32_bf16 v[126:129], v[164:167], v[192:195], v[126:129]
	v_mfma_f32_16x16x32_bf16 v[114:117], v[156:159], v[204:207], v[114:117]
	v_mfma_f32_16x16x32_bf16 v[110:113], v[164:167], v[204:207], v[110:113]
	v_mfma_f32_16x16x32_bf16 v[98:101], v[156:159], v[212:215], v[98:101]
	v_mfma_f32_16x16x32_bf16 v[94:97], v[164:167], v[212:215], v[94:97]
	v_mfma_f32_16x16x32_bf16 v[82:85], v[156:159], v[236:239], v[82:85]
	v_mfma_f32_16x16x32_bf16 v[78:81], v[164:167], v[236:239], v[78:81]
	v_mfma_f32_16x16x32_bf16 v[122:125], v[168:171], v[188:191], v[122:125]
	v_mfma_f32_16x16x32_bf16 v[118:121], v[180:183], v[188:191], v[118:121]
	v_mfma_f32_16x16x32_bf16 v[106:109], v[168:171], v[200:203], v[106:109]
	v_mfma_f32_16x16x32_bf16 v[102:105], v[180:183], v[200:203], v[102:105]
	v_mfma_f32_16x16x32_bf16 v[90:93], v[168:171], v[208:211], v[90:93]
	v_mfma_f32_16x16x32_bf16 v[86:89], v[180:183], v[208:211], v[86:89]
	v_mfma_f32_16x16x32_bf16 v[74:77], v[168:171], v[216:219], v[74:77]
	v_mfma_f32_16x16x32_bf16 v[70:73], v[180:183], v[216:219], v[70:73]
	v_mfma_f32_16x16x32_bf16 v[122:125], v[172:175], v[192:195], v[122:125]
	v_mfma_f32_16x16x32_bf16 v[118:121], v[184:187], v[192:195], v[118:121]
	v_mfma_f32_16x16x32_bf16 v[106:109], v[172:175], v[204:207], v[106:109]
	v_mfma_f32_16x16x32_bf16 v[102:105], v[184:187], v[204:207], v[102:105]
	v_mfma_f32_16x16x32_bf16 v[90:93], v[172:175], v[212:215], v[90:93]
	v_mfma_f32_16x16x32_bf16 v[86:89], v[184:187], v[212:215], v[86:89]
	v_mfma_f32_16x16x32_bf16 v[74:77], v[172:175], v[236:239], v[74:77]
	v_mfma_f32_16x16x32_bf16 v[70:73], v[184:187], v[236:239], v[70:73]
	s_setprio 0
	s_barrier
	s_add_i32 s93, s93, s89
	v_lshl_add_u64 v[196:197], s[8:9], 0, v[142:143]
	s_mov_b32 m0, s93
	ds_read_b128 v[188:191], v178 offset:16384
	ds_read_b128 v[192:195], v178 offset:17408
	ds_read_b128 v[200:203], v178 offset:18432
	ds_read_b128 v[204:207], v178 offset:19456
	ds_read_b128 v[208:211], v178 offset:20480
	ds_read_b128 v[212:215], v178 offset:21504
	ds_read_b128 v[216:219], v178 offset:22528
	ds_read_b128 v[236:239], v178 offset:23552
	global_load_lds_dwordx4 v[196:197], off
	s_add_i32 m0, s93, 0x2000
	s_add_u32 vcc_lo, s8, 0x80000
	v_lshl_add_u64 v[228:229], s[8:9], 0, v[2:3]
	s_addc_u32 vcc_hi, s9, 0
	s_add_i32 s93, s97, s89
	global_load_lds_dwordx4 v[228:229], off
	v_lshl_add_u64 v[230:231], vcc, 0, v[142:143]
	s_mov_b32 m0, s93
	v_lshl_add_u64 v[240:241], s[10:11], 0, v[136:137]
	global_load_lds_dwordx4 v[230:231], off
	v_lshl_add_u64 v[230:231], vcc, 0, v[2:3]
	s_add_i32 m0, s93, 0x2000
	s_nop 0
	global_load_lds_dwordx4 v[230:231], off
	v_lshl_add_u64 v[230:231], s[10:11], 0, v[144:145]
	s_mov_b32 m0, s90
	s_nop 0
	global_load_lds_dwordx4 v[230:231], off
	s_mov_b32 m0, s91
	s_nop 0
	global_load_lds_dwordx4 v[240:241], off
	s_waitcnt vmcnt(8)
	s_waitcnt lgkmcnt(0)
	s_barrier
; #define PG8_STAGE(bufoff, gbase, voff) do { _Pragma("unroll") for (int _i = 0; _i < 2; ++_i) \
;         __builtin_amdgcn_global_load_lds((const unsigned*)((const char*)(gbase) + (voff)[_i]), (PG8_LAS unsigned*)(lds + (bufoff) + ldsw + _i * 8192), 16, 0, 0); } while (0)
; #define PG8_LDA(dst, b, h) do { _Pragma("unroll") for (int m = 0; m < 4; ++m) _Pragma("unroll") for (int k = 0; k < 2; ++k) dst[m][k] = *(const PG8_LAS bf16x8*)(lds + PG8_SA(b, h) + aoff + m * 2048 + k * 1024); } while (0)
; #define PG8_LDB(dst, b, h) do { _Pragma("unroll") for (int n = 0; n < 2; ++n) _Pragma("unroll") for (int k = 0; k < 2; ++k) dst[n][k] = *(const PG8_LAS bf16x8*)(lds + PG8_SB(b, h) + boff + n * 2048 + k * 1024); } while (0)
; #define PG8_MMA(ai, bj, At, Bt) do { __builtin_amdgcn_s_setprio(1); _Pragma("unroll") for (int m = 0; m < 4; ++m) _Pragma("unroll") for (int n = 0; n < 2; ++n) _Pragma("unroll") for (int k = 0; k < 2; ++k) \
;         acc[ai][bj][m][n] = __builtin_amdgcn_mfma_f32_16x16x32_bf16(Bt[n][k], At[m][k], acc[ai][bj][m][n], 0, 0, 0); __builtin_amdgcn_s_setprio(0); } while (0)
; #define PG8_WAIT_V(n) asm volatile("s_waitcnt vmcnt(" #n ")" ::: "memory")
; #define PG8_WAIT_L(n) asm volatile("s_waitcnt lgkmcnt(" #n ")" ::: "memory")
; #define PG8_BAR __builtin_amdgcn_s_barrier()
; #define PG8_SCHED __builtin_amdgcn_sched_barrier(0)
; template <class Epi, class Sched, bool ALIGN_EPI = false, bool SP2 = false>
; __device__ __forceinline__ void gemm_phase(PG8_LAS unsigned char* lds, const Gemm g, const Sched& S, const Epi& E) {
;     ...
;             PG8_WAIT_V(8); PG8_WAIT_L(0); PG8_BAR; PG8_MMA(1, 0, At, B0); PG8_MMA(1, 1, At, B1); PG8_BAR; PG8_SCHED;
;             PG8_LDB(B0, 1, 0); PG8_LDB(B1, 1, 1); PG8_SCHED; PG8_LDA(At, 1, 0); PG8_STAGE(PG8_SA(0, 1), a2 + hstep, voffA);
;             PG8_WAIT_V(8); PG8_WAIT_L(0); PG8_BAR; PG8_MMA(0, 0, At, B0); PG8_MMA(0, 1, At, B1); PG8_BAR; PG8_SCHED;
	s_setprio 1
	v_mfma_f32_16x16x32_bf16 v[66:69], v[152:155], v[188:191], v[66:69]
	v_mfma_f32_16x16x32_bf16 v[62:65], v[160:163], v[188:191], v[62:65]
	v_mfma_f32_16x16x32_bf16 v[50:53], v[152:155], v[200:203], v[50:53]
	v_mfma_f32_16x16x32_bf16 v[46:49], v[160:163], v[200:203], v[46:49]
	v_mfma_f32_16x16x32_bf16 v[34:37], v[152:155], v[208:211], v[34:37]
	v_mfma_f32_16x16x32_bf16 v[30:33], v[160:163], v[208:211], v[30:33]
	v_mfma_f32_16x16x32_bf16 v[18:21], v[152:155], v[216:219], v[18:21]
	v_mfma_f32_16x16x32_bf16 v[14:17], v[160:163], v[216:219], v[14:17]
	v_mfma_f32_16x16x32_bf16 v[66:69], v[156:159], v[192:195], v[66:69]
	v_mfma_f32_16x16x32_bf16 v[62:65], v[164:167], v[192:195], v[62:65]
	v_mfma_f32_16x16x32_bf16 v[50:53], v[156:159], v[204:207], v[50:53]
	v_mfma_f32_16x16x32_bf16 v[46:49], v[164:167], v[204:207], v[46:49]
	v_mfma_f32_16x16x32_bf16 v[34:37], v[156:159], v[212:215], v[34:37]
	v_mfma_f32_16x16x32_bf16 v[30:33], v[164:167], v[212:215], v[30:33]
	v_mfma_f32_16x16x32_bf16 v[18:21], v[156:159], v[236:239], v[18:21]
	v_mfma_f32_16x16x32_bf16 v[14:17], v[164:167], v[236:239], v[14:17]
	v_mfma_f32_16x16x32_bf16 v[58:61], v[168:171], v[188:191], v[58:61]
	v_mfma_f32_16x16x32_bf16 v[54:57], v[180:183], v[188:191], v[54:57]
	v_mfma_f32_16x16x32_bf16 v[42:45], v[168:171], v[200:203], v[42:45]
	v_mfma_f32_16x16x32_bf16 v[38:41], v[180:183], v[200:203], v[38:41]
	v_mfma_f32_16x16x32_bf16 v[26:29], v[168:171], v[208:211], v[26:29]
	v_mfma_f32_16x16x32_bf16 v[22:25], v[180:183], v[208:211], v[22:25]
	v_mfma_f32_16x16x32_bf16 v[10:13], v[168:171], v[216:219], v[10:13]
	v_mfma_f32_16x16x32_bf16 v[6:9], v[180:183], v[216:219], v[6:9]
	v_mfma_f32_16x16x32_bf16 v[58:61], v[172:175], v[192:195], v[58:61]
	v_mfma_f32_16x16x32_bf16 v[54:57], v[184:187], v[192:195], v[54:57]
	v_mfma_f32_16x16x32_bf16 v[42:45], v[172:175], v[204:207], v[42:45]
	v_mfma_f32_16x16x32_bf16 v[38:41], v[184:187], v[204:207], v[38:41]
	v_mfma_f32_16x16x32_bf16 v[26:29], v[172:175], v[212:215], v[26:29]
	v_mfma_f32_16x16x32_bf16 v[22:25], v[184:187], v[212:215], v[22:25]
	v_mfma_f32_16x16x32_bf16 v[10:13], v[172:175], v[236:239], v[10:13]
	v_mfma_f32_16x16x32_bf16 v[6:9], v[184:187], v[236:239], v[6:9]
	s_setprio 0
	s_barrier
	s_add_i32 s93, 0, 0x18000
	v_add_u32_e32 v151, s93, v135
	s_add_i32 s97, 0, 0x1c000
	ds_read_b128 v[152:155], v151
	ds_read_b128 v[156:159], v151 offset:1024
	ds_read_b128 v[160:163], v151 offset:2048
	ds_read_b128 v[164:167], v151 offset:3072
	v_add_u32_e32 v151, s97, v135
	ds_read_b128 v[168:171], v151
	ds_read_b128 v[172:175], v151 offset:1024
	ds_read_b128 v[180:183], v151 offset:2048
	ds_read_b128 v[184:187], v151 offset:3072
	s_add_u32 s10, s10, 0x80000
	s_addc_u32 s11, s11, 0
	s_mov_b32 m0, s18
	v_lshl_add_u64 v[242:243], s[10:11], 0, v[144:145]
	ds_read_b128 v[188:191], v178 offset:32768
	ds_read_b128 v[192:195], v178 offset:33792
	ds_read_b128 v[200:203], v178 offset:34816
	ds_read_b128 v[204:207], v178 offset:35840
	ds_read_b128 v[208:211], v178 offset:36864
	ds_read_b128 v[212:215], v178 offset:37888
	ds_read_b128 v[216:219], v178 offset:38912
	ds_read_b128 v[236:239], v178 offset:39936
	global_load_lds_dwordx4 v[242:243], off
	v_lshl_add_u64 v[242:243], s[10:11], 0, v[136:137]
	s_mov_b32 m0, s19
	s_nop 0
	global_load_lds_dwordx4 v[242:243], off
	s_waitcnt vmcnt(8)
	s_waitcnt lgkmcnt(0)
	s_barrier
	s_setprio 1
	v_mfma_f32_16x16x32_bf16 v[130:133], v[152:155], v[188:191], v[130:133]
	v_mfma_f32_16x16x32_bf16 v[126:129], v[160:163], v[188:191], v[126:129]
	v_mfma_f32_16x16x32_bf16 v[114:117], v[152:155], v[200:203], v[114:117]
	v_mfma_f32_16x16x32_bf16 v[110:113], v[160:163], v[200:203], v[110:113]
	v_mfma_f32_16x16x32_bf16 v[98:101], v[152:155], v[208:211], v[98:101]
	v_mfma_f32_16x16x32_bf16 v[94:97], v[160:163], v[208:211], v[94:97]
	v_mfma_f32_16x16x32_bf16 v[82:85], v[152:155], v[216:219], v[82:85]
	v_mfma_f32_16x16x32_bf16 v[78:81], v[160:163], v[216:219], v[78:81]
	v_mfma_f32_16x16x32_bf16 v[130:133], v[156:159], v[192:195], v[130:133]
	v_mfma_f32_16x16x32_bf16 v[126:129], v[164:167], v[192:195], v[126:129]
	v_mfma_f32_16x16x32_bf16 v[114:117], v[156:159], v[204:207], v[114:117]
	v_mfma_f32_16x16x32_bf16 v[110:113], v[164:167], v[204:207], v[110:113]
	v_mfma_f32_16x16x32_bf16 v[98:101], v[156:159], v[212:215], v[98:101]
	v_mfma_f32_16x16x32_bf16 v[94:97], v[164:167], v[212:215], v[94:97]
	v_mfma_f32_16x16x32_bf16 v[82:85], v[156:159], v[236:239], v[82:85]
	v_mfma_f32_16x16x32_bf16 v[78:81], v[164:167], v[236:239], v[78:81]
	v_mfma_f32_16x16x32_bf16 v[122:125], v[168:171], v[188:191], v[122:125]
	v_mfma_f32_16x16x32_bf16 v[118:121], v[180:183], v[188:191], v[118:121]
	v_mfma_f32_16x16x32_bf16 v[106:109], v[168:171], v[200:203], v[106:109]
	v_mfma_f32_16x16x32_bf16 v[102:105], v[180:183], v[200:203], v[102:105]
	v_mfma_f32_16x16x32_bf16 v[90:93], v[168:171], v[208:211], v[90:93]
	v_mfma_f32_16x16x32_bf16 v[86:89], v[180:183], v[208:211], v[86:89]
	v_mfma_f32_16x16x32_bf16 v[74:77], v[168:171], v[216:219], v[74:77]
	v_mfma_f32_16x16x32_bf16 v[70:73], v[180:183], v[216:219], v[70:73]
	v_mfma_f32_16x16x32_bf16 v[122:125], v[172:175], v[192:195], v[122:125]
	v_mfma_f32_16x16x32_bf16 v[118:121], v[184:187], v[192:195], v[118:121]
	v_mfma_f32_16x16x32_bf16 v[106:109], v[172:175], v[204:207], v[106:109]
	v_mfma_f32_16x16x32_bf16 v[102:105], v[184:187], v[204:207], v[102:105]
	v_mfma_f32_16x16x32_bf16 v[90:93], v[172:175], v[212:215], v[90:93]
	v_mfma_f32_16x16x32_bf16 v[86:89], v[184:187], v[212:215], v[86:89]
	v_mfma_f32_16x16x32_bf16 v[74:77], v[172:175], v[236:239], v[74:77]
	v_mfma_f32_16x16x32_bf16 v[70:73], v[184:187], v[236:239], v[70:73]
	s_setprio 0
	s_barrier
; #define PG8_STAGE(bufoff, gbase, voff) do { _Pragma("unroll") for (int _i = 0; _i < 2; ++_i) \
;         __builtin_amdgcn_global_load_lds((const unsigned*)((const char*)(gbase) + (voff)[_i]), (PG8_LAS unsigned*)(lds + (bufoff) + ldsw + _i * 8192), 16, 0, 0); } while (0)
; #define PG8_LDA(dst, b, h) do { _Pragma("unroll") for (int m = 0; m < 4; ++m) _Pragma("unroll") for (int k = 0; k < 2; ++k) dst[m][k] = *(const PG8_LAS bf16x8*)(lds + PG8_SA(b, h) + aoff + m * 2048 + k * 1024); } while (0)
; #define PG8_MMA(ai, bj, At, Bt) do { __builtin_amdgcn_s_setprio(1); _Pragma("unroll") for (int m = 0; m < 4; ++m) _Pragma("unroll") for (int n = 0; n < 2; ++n) _Pragma("unroll") for (int k = 0; k < 2; ++k) \
;         acc[ai][bj][m][n] = __builtin_amdgcn_mfma_f32_16x16x32_bf16(Bt[n][k], At[m][k], acc[ai][bj][m][n], 0, 0, 0); __builtin_amdgcn_s_setprio(0); } while (0)
; #define PG8_WAIT_V(n) asm volatile("s_waitcnt vmcnt(" #n ")" ::: "memory")
; #define PG8_WAIT_L(n) asm volatile("s_waitcnt lgkmcnt(" #n ")" ::: "memory")
; #define PG8_BAR __builtin_amdgcn_s_barrier()
; #define PG8_SCHED __builtin_amdgcn_sched_barrier(0)
; template <class Epi, class Sched, bool ALIGN_EPI = false, bool SP2 = false>
; __device__ __forceinline__ void gemm_phase(PG8_LAS unsigned char* lds, const Gemm g, const Sched& S, const Epi& E) {
;     ...
;             PG8_LDA(At, 1, 1); PG8_STAGE(PG8_SB(1, 0), b3, voffB); PG8_STAGE(PG8_SB(1, 1), b3 + hstep, voffB); PG8_STAGE(PG8_SA(1, 0), a3, voffA);
;             PG8_WAIT_V(8); PG8_WAIT_L(0); PG8_BAR; PG8_MMA(1, 0, At, B0); PG8_MMA(1, 1, At, B1); PG8_BAR; PG8_SCHED;
	s_add_i32 s10, s93, s89
	v_lshl_add_u64 v[196:197], v[196:197], 0, s[64:65]
	s_mov_b32 m0, s10
	ds_read_b128 v[188:191], v178 offset:49152
	ds_read_b128 v[192:195], v178 offset:50176
	ds_read_b128 v[200:203], v178 offset:51200
	ds_read_b128 v[204:207], v178 offset:52224
	ds_read_b128 v[208:211], v178 offset:53248
	ds_read_b128 v[212:215], v178 offset:54272
	ds_read_b128 v[216:219], v178 offset:55296
	ds_read_b128 v[236:239], v178 offset:56320
	global_load_lds_dwordx4 v[196:197], off
	s_add_i32 m0, s10, 0x2000
	s_add_u32 s8, s8, 0x80080
	v_lshl_add_u64 v[196:197], v[228:229], 0, s[64:65]
	s_addc_u32 s9, s9, 0
	s_add_i32 s10, s97, s89
	global_load_lds_dwordx4 v[196:197], off
	v_lshl_add_u64 v[196:197], s[8:9], 0, v[142:143]
	s_mov_b32 m0, s10
	s_nop 0
	global_load_lds_dwordx4 v[196:197], off
	v_lshl_add_u64 v[196:197], s[8:9], 0, v[2:3]
	s_add_i32 m0, s10, 0x2000
	s_nop 0
	global_load_lds_dwordx4 v[196:197], off
	v_lshl_add_u64 v[196:197], v[230:231], 0, s[64:65]
	s_mov_b32 m0, s22
	s_nop 0
	global_load_lds_dwordx4 v[196:197], off
	v_lshl_add_u64 v[196:197], v[240:241], 0, s[64:65]
	s_mov_b32 m0, s23
	s_nop 0
	global_load_lds_dwordx4 v[196:197], off
	s_waitcnt vmcnt(8)
	s_waitcnt lgkmcnt(0)
	s_barrier
	s_setprio 1
	v_mfma_f32_16x16x32_bf16 v[66:69], v[152:155], v[188:191], v[66:69]
	v_mfma_f32_16x16x32_bf16 v[62:65], v[160:163], v[188:191], v[62:65]
	v_mfma_f32_16x16x32_bf16 v[50:53], v[152:155], v[200:203], v[50:53]
	v_mfma_f32_16x16x32_bf16 v[46:49], v[160:163], v[200:203], v[46:49]
	v_mfma_f32_16x16x32_bf16 v[34:37], v[152:155], v[208:211], v[34:37]
	v_mfma_f32_16x16x32_bf16 v[30:33], v[160:163], v[208:211], v[30:33]
	v_mfma_f32_16x16x32_bf16 v[18:21], v[152:155], v[216:219], v[18:21]
	v_mfma_f32_16x16x32_bf16 v[14:17], v[160:163], v[216:219], v[14:17]
	v_mfma_f32_16x16x32_bf16 v[66:69], v[156:159], v[192:195], v[66:69]
	v_mfma_f32_16x16x32_bf16 v[62:65], v[164:167], v[192:195], v[62:65]
	v_mfma_f32_16x16x32_bf16 v[50:53], v[156:159], v[204:207], v[50:53]
	v_mfma_f32_16x16x32_bf16 v[46:49], v[164:167], v[204:207], v[46:49]
	v_mfma_f32_16x16x32_bf16 v[34:37], v[156:159], v[212:215], v[34:37]
	v_mfma_f32_16x16x32_bf16 v[30:33], v[164:167], v[212:215], v[30:33]
	v_mfma_f32_16x16x32_bf16 v[18:21], v[156:159], v[236:239], v[18:21]
	v_mfma_f32_16x16x32_bf16 v[14:17], v[164:167], v[236:239], v[14:17]
	v_mfma_f32_16x16x32_bf16 v[58:61], v[168:171], v[188:191], v[58:61]
	v_mfma_f32_16x16x32_bf16 v[54:57], v[180:183], v[188:191], v[54:57]
	v_mfma_f32_16x16x32_bf16 v[42:45], v[168:171], v[200:203], v[42:45]
	v_mfma_f32_16x16x32_bf16 v[38:41], v[180:183], v[200:203], v[38:41]
	v_mfma_f32_16x16x32_bf16 v[26:29], v[168:171], v[208:211], v[26:29]
	v_mfma_f32_16x16x32_bf16 v[22:25], v[180:183], v[208:211], v[22:25]
	v_mfma_f32_16x16x32_bf16 v[10:13], v[168:171], v[216:219], v[10:13]
	v_mfma_f32_16x16x32_bf16 v[6:9], v[180:183], v[216:219], v[6:9]
	v_mfma_f32_16x16x32_bf16 v[58:61], v[172:175], v[192:195], v[58:61]
	v_mfma_f32_16x16x32_bf16 v[54:57], v[184:187], v[192:195], v[54:57]
	v_mfma_f32_16x16x32_bf16 v[42:45], v[172:175], v[204:207], v[42:45]
	v_mfma_f32_16x16x32_bf16 v[38:41], v[184:187], v[204:207], v[38:41]
	v_mfma_f32_16x16x32_bf16 v[26:29], v[172:175], v[212:215], v[26:29]
	v_mfma_f32_16x16x32_bf16 v[22:25], v[184:187], v[212:215], v[22:25]
	v_mfma_f32_16x16x32_bf16 v[10:13], v[172:175], v[236:239], v[10:13]
	v_mfma_f32_16x16x32_bf16 v[6:9], v[184:187], v[236:239], v[6:9]
	s_setprio 0
	s_barrier
	s_add_i32 s85, s85, 2
	s_add_u32 s6, s6, 0x100
	s_addc_u32 s7, s7, 0
	s_add_u32 s73, s73, 0x100
	s_addc_u32 s84, s84, 0
	s_cmp_gt_u32 s85, 29
	s_cbranch_scc0 .LBB0_161
	s_and_b64 vcc, exec, s[26:27]
	s_cbranch_vccz .LBB0_164
	s_barrier

; #define PG8_STAGE(bufoff, gbase, voff) do { _Pragma("unroll") for (int _i = 0; _i < 2; ++_i) \
;         __builtin_amdgcn_global_load_lds((const unsigned*)((const char*)(gbase) + (voff)[_i]), (PG8_LAS unsigned*)(lds + (bufoff) + ldsw + _i * 8192), 16, 0, 0); } while (0)
; #define PG8_LDA(dst, b, h) do { _Pragma("unroll") for (int m = 0; m < 4; ++m) _Pragma("unroll") for (int k = 0; k < 2; ++k) dst[m][k] = *(const PG8_LAS bf16x8*)(lds + PG8_SA(b, h) + aoff + m * 2048 + k * 1024); } while (0)
; #define PG8_LDB(dst, b, h) do { _Pragma("unroll") for (int n = 0; n < 2; ++n) _Pragma("unroll") for (int k = 0; k < 2; ++k) dst[n][k] = *(const PG8_LAS bf16x8*)(lds + PG8_SB(b, h) + boff + n * 2048 + k * 1024); } while (0)
; #define PG8_MMA(ai, bj, At, Bt) do { __builtin_amdgcn_s_setprio(1); _Pragma("unroll") for (int m = 0; m < 4; ++m) _Pragma("unroll") for (int n = 0; n < 2; ++n) _Pragma("unroll") for (int k = 0; k < 2; ++k) \
;         acc[ai][bj][m][n] = __builtin_amdgcn_mfma_f32_16x16x32_bf16(Bt[n][k], At[m][k], acc[ai][bj][m][n], 0, 0, 0); __builtin_amdgcn_s_setprio(0); } while (0)
; #define PG8_WAIT_V(n) asm volatile("s_waitcnt vmcnt(" #n ")" ::: "memory")
; #define PG8_WAIT_L(n) asm volatile("s_waitcnt lgkmcnt(" #n ")" ::: "memory")
; #define PG8_BAR __builtin_amdgcn_s_barrier()
; #define PG8_SCHED __builtin_amdgcn_sched_barrier(0)
; template <class Epi, class Sched, bool ALIGN_EPI = false, bool SP2 = false>
; __device__ __forceinline__ void gemm_phase(PG8_LAS unsigned char* lds, const Gemm g, const Sched& S, const Epi& E) {
;     ...
;             PG8_LDB(B0, 0, 0); PG8_LDB(B1, 0, 1); PG8_SCHED; PG8_LDA(At, 0, 0); PG8_STAGE(PG8_SA(1, 1), a1 + hstep, voffA);
;             PG8_WAIT_V(8); PG8_WAIT_L(0); PG8_BAR; PG8_MMA(0, 0, At, B0); PG8_MMA(0, 1, At, B1); PG8_BAR; PG8_SCHED;
;             PG8_LDA(At, 0, 1); PG8_STAGE(PG8_SB(0, 0), b2, voffB); PG8_STAGE(PG8_SB(0, 1), b2 + hstep, voffB); PG8_STAGE(PG8_SA(0, 0), a2, voffA);
;             PG8_WAIT_V(8); PG8_WAIT_L(0); PG8_BAR; PG8_MMA(1, 0, At, B0); PG8_MMA(1, 1, At, B1); PG8_BAR; PG8_SCHED;
.LBB0_1390:
	s_add_u32 s26, s8, 0xfffc0080
	s_addc_u32 s27, s9, -1
	s_add_i32 s90, 0, 0x10000
	s_cmp_eq_u32 s89, 12
	s_cselect_b32 s31, s15, s27
	s_cselect_b32 s30, s81, s26
	s_cselect_b32 s27, s17, s88
	s_cselect_b32 s26, s84, s85
	s_add_i32 s93, 0, 0x14000
	v_add_u32_e32 v154, s90, v135
	v_add_u32_e32 v170, s93, v135
	ds_read_b128 v[142:145], v154
	ds_read_b128 v[146:149], v154 offset:1024
	ds_read_b128 v[150:153], v154 offset:2048
	ds_read_b128 v[154:157], v154 offset:3072
	ds_read_b128 v[158:161], v170
	ds_read_b128 v[162:165], v170 offset:1024
	ds_read_b128 v[166:169], v170 offset:2048
	ds_read_b128 v[170:173], v170 offset:3072
	v_lshl_add_u64 v[174:175], s[8:9], 0, v[180:181]
	s_add_i32 m0, s44, 0xc000
	ds_read_b128 v[184:187], v236
	ds_read_b128 v[188:191], v236 offset:1024
	ds_read_b128 v[192:195], v236 offset:2048
	ds_read_b128 v[200:203], v236 offset:3072
	ds_read_b128 v[204:207], v236 offset:4096
	ds_read_b128 v[208:211], v236 offset:5120
	ds_read_b128 v[212:215], v236 offset:6144
	ds_read_b128 v[216:219], v236 offset:7168
	global_load_lds_dwordx4 v[174:175], off
	v_lshl_add_u64 v[174:175], s[8:9], 0, v[182:183]
	s_add_i32 m0, s44, 0xe000
	s_nop 0
	global_load_lds_dwordx4 v[174:175], off
	s_waitcnt vmcnt(8)
	s_waitcnt lgkmcnt(0)
	s_barrier
	s_setprio 1
	v_mfma_f32_16x16x32_bf16 v[130:133], v[142:145], v[184:187], v[130:133]
	v_mfma_f32_16x16x32_bf16 v[126:129], v[150:153], v[184:187], v[126:129]
	v_mfma_f32_16x16x32_bf16 v[114:117], v[142:145], v[192:195], v[114:117]
	v_mfma_f32_16x16x32_bf16 v[110:113], v[150:153], v[192:195], v[110:113]
	v_mfma_f32_16x16x32_bf16 v[98:101], v[142:145], v[204:207], v[98:101]
	v_mfma_f32_16x16x32_bf16 v[94:97], v[150:153], v[204:207], v[94:97]
	v_mfma_f32_16x16x32_bf16 v[82:85], v[142:145], v[212:215], v[82:85]
	v_mfma_f32_16x16x32_bf16 v[78:81], v[150:153], v[212:215], v[78:81]
	v_mfma_f32_16x16x32_bf16 v[130:133], v[146:149], v[188:191], v[130:133]
	v_mfma_f32_16x16x32_bf16 v[126:129], v[154:157], v[188:191], v[126:129]
	v_mfma_f32_16x16x32_bf16 v[114:117], v[146:149], v[200:203], v[114:117]
	v_mfma_f32_16x16x32_bf16 v[110:113], v[154:157], v[200:203], v[110:113]
	v_mfma_f32_16x16x32_bf16 v[98:101], v[146:149], v[208:211], v[98:101]
	v_mfma_f32_16x16x32_bf16 v[94:97], v[154:157], v[208:211], v[94:97]
	v_mfma_f32_16x16x32_bf16 v[82:85], v[146:149], v[216:219], v[82:85]
	v_mfma_f32_16x16x32_bf16 v[78:81], v[154:157], v[216:219], v[78:81]
	v_mfma_f32_16x16x32_bf16 v[122:125], v[158:161], v[184:187], v[122:125]
	v_mfma_f32_16x16x32_bf16 v[118:121], v[166:169], v[184:187], v[118:121]
	v_mfma_f32_16x16x32_bf16 v[106:109], v[158:161], v[192:195], v[106:109]
	v_mfma_f32_16x16x32_bf16 v[102:105], v[166:169], v[192:195], v[102:105]
	v_mfma_f32_16x16x32_bf16 v[90:93], v[158:161], v[204:207], v[90:93]
	v_mfma_f32_16x16x32_bf16 v[86:89], v[166:169], v[204:207], v[86:89]
	v_mfma_f32_16x16x32_bf16 v[74:77], v[158:161], v[212:215], v[74:77]
	v_mfma_f32_16x16x32_bf16 v[70:73], v[166:169], v[212:215], v[70:73]
	v_mfma_f32_16x16x32_bf16 v[122:125], v[162:165], v[188:191], v[122:125]
	v_mfma_f32_16x16x32_bf16 v[118:121], v[170:173], v[188:191], v[118:121]
	v_mfma_f32_16x16x32_bf16 v[106:109], v[162:165], v[200:203], v[106:109]
	v_mfma_f32_16x16x32_bf16 v[102:105], v[170:173], v[200:203], v[102:105]
	v_mfma_f32_16x16x32_bf16 v[90:93], v[162:165], v[208:211], v[90:93]
	v_mfma_f32_16x16x32_bf16 v[86:89], v[170:173], v[208:211], v[86:89]
	v_mfma_f32_16x16x32_bf16 v[74:77], v[162:165], v[216:219], v[74:77]
	v_mfma_f32_16x16x32_bf16 v[70:73], v[170:173], v[216:219], v[70:73]
	s_setprio 0
	s_barrier
	s_add_i32 s90, s90, s39
	v_lshl_add_u64 v[174:175], s[26:27], 0, v[176:177]
	s_mov_b32 m0, s90
	ds_read_b128 v[184:187], v236 offset:16384
	ds_read_b128 v[188:191], v236 offset:17408
	ds_read_b128 v[192:195], v236 offset:18432
	ds_read_b128 v[200:203], v236 offset:19456
	ds_read_b128 v[204:207], v236 offset:20480
	ds_read_b128 v[208:211], v236 offset:21504
	ds_read_b128 v[212:215], v236 offset:22528
	ds_read_b128 v[216:219], v236 offset:23552
	global_load_lds_dwordx4 v[174:175], off
	s_add_i32 m0, s90, 0x2000
	s_add_u32 s90, s26, 0x40000
	v_lshl_add_u64 v[196:197], s[26:27], 0, v[2:3]
	s_addc_u32 s91, s27, 0
	s_add_i32 s93, s93, s39
	global_load_lds_dwordx4 v[196:197], off
	v_lshl_add_u64 v[228:229], s[90:91], 0, v[176:177]
	s_mov_b32 m0, s93
	v_lshl_add_u64 v[230:231], s[30:31], 0, v[136:137]
	global_load_lds_dwordx4 v[228:229], off
	v_lshl_add_u64 v[228:229], s[90:91], 0, v[2:3]
	s_add_i32 m0, s93, 0x2000
	s_nop 0
	global_load_lds_dwordx4 v[228:229], off
	v_lshl_add_u64 v[228:229], s[30:31], 0, v[178:179]
	s_mov_b32 m0, s44
	s_nop 0
	global_load_lds_dwordx4 v[228:229], off
	s_mov_b32 m0, s45
	s_nop 0
	global_load_lds_dwordx4 v[230:231], off
	s_waitcnt vmcnt(8)
	s_waitcnt lgkmcnt(0)
	s_barrier
; #define PG8_STAGE(bufoff, gbase, voff) do { _Pragma("unroll") for (int _i = 0; _i < 2; ++_i) \
;         __builtin_amdgcn_global_load_lds((const unsigned*)((const char*)(gbase) + (voff)[_i]), (PG8_LAS unsigned*)(lds + (bufoff) + ldsw + _i * 8192), 16, 0, 0); } while (0)
; #define PG8_LDA(dst, b, h) do { _Pragma("unroll") for (int m = 0; m < 4; ++m) _Pragma("unroll") for (int k = 0; k < 2; ++k) dst[m][k] = *(const PG8_LAS bf16x8*)(lds + PG8_SA(b, h) + aoff + m * 2048 + k * 1024); } while (0)
; #define PG8_LDB(dst, b, h) do { _Pragma("unroll") for (int n = 0; n < 2; ++n) _Pragma("unroll") for (int k = 0; k < 2; ++k) dst[n][k] = *(const PG8_LAS bf16x8*)(lds + PG8_SB(b, h) + boff + n * 2048 + k * 1024); } while (0)
; #define PG8_MMA(ai, bj, At, Bt) do { __builtin_amdgcn_s_setprio(1); _Pragma("unroll") for (int m = 0; m < 4; ++m) _Pragma("unroll") for (int n = 0; n < 2; ++n) _Pragma("unroll") for (int k = 0; k < 2; ++k) \
;         acc[ai][bj][m][n] = __builtin_amdgcn_mfma_f32_16x16x32_bf16(Bt[n][k], At[m][k], acc[ai][bj][m][n], 0, 0, 0); __builtin_amdgcn_s_setprio(0); } while (0)
; #define PG8_WAIT_V(n) asm volatile("s_waitcnt vmcnt(" #n ")" ::: "memory")
; #define PG8_WAIT_L(n) asm volatile("s_waitcnt lgkmcnt(" #n ")" ::: "memory")
; #define PG8_BAR __builtin_amdgcn_s_barrier()
; #define PG8_SCHED __builtin_amdgcn_sched_barrier(0)
; template <class Epi, class Sched, bool ALIGN_EPI = false, bool SP2 = false>
; __device__ __forceinline__ void gemm_phase(PG8_LAS unsigned char* lds, const Gemm g, const Sched& S, const Epi& E) {
;     ...
;             PG8_WAIT_V(8); PG8_WAIT_L(0); PG8_BAR; PG8_MMA(1, 0, At, B0); PG8_MMA(1, 1, At, B1); PG8_BAR; PG8_SCHED;
;             PG8_LDB(B0, 1, 0); PG8_LDB(B1, 1, 1); PG8_SCHED; PG8_LDA(At, 1, 0); PG8_STAGE(PG8_SA(0, 1), a2 + hstep, voffA);
;             PG8_WAIT_V(8); PG8_WAIT_L(0); PG8_BAR; PG8_MMA(0, 0, At, B0); PG8_MMA(0, 1, At, B1); PG8_BAR; PG8_SCHED;
	s_setprio 1
	v_mfma_f32_16x16x32_bf16 v[66:69], v[142:145], v[184:187], v[66:69]
	v_mfma_f32_16x16x32_bf16 v[62:65], v[150:153], v[184:187], v[62:65]
	v_mfma_f32_16x16x32_bf16 v[50:53], v[142:145], v[192:195], v[50:53]
	v_mfma_f32_16x16x32_bf16 v[46:49], v[150:153], v[192:195], v[46:49]
	v_mfma_f32_16x16x32_bf16 v[34:37], v[142:145], v[204:207], v[34:37]
	v_mfma_f32_16x16x32_bf16 v[30:33], v[150:153], v[204:207], v[30:33]
	v_mfma_f32_16x16x32_bf16 v[18:21], v[142:145], v[212:215], v[18:21]
	v_mfma_f32_16x16x32_bf16 v[14:17], v[150:153], v[212:215], v[14:17]
	v_mfma_f32_16x16x32_bf16 v[66:69], v[146:149], v[188:191], v[66:69]
	v_mfma_f32_16x16x32_bf16 v[62:65], v[154:157], v[188:191], v[62:65]
	v_mfma_f32_16x16x32_bf16 v[50:53], v[146:149], v[200:203], v[50:53]
	v_mfma_f32_16x16x32_bf16 v[46:49], v[154:157], v[200:203], v[46:49]
	v_mfma_f32_16x16x32_bf16 v[34:37], v[146:149], v[208:211], v[34:37]
	v_mfma_f32_16x16x32_bf16 v[30:33], v[154:157], v[208:211], v[30:33]
	v_mfma_f32_16x16x32_bf16 v[18:21], v[146:149], v[216:219], v[18:21]
	v_mfma_f32_16x16x32_bf16 v[14:17], v[154:157], v[216:219], v[14:17]
	v_mfma_f32_16x16x32_bf16 v[58:61], v[158:161], v[184:187], v[58:61]
	v_mfma_f32_16x16x32_bf16 v[54:57], v[166:169], v[184:187], v[54:57]
	v_mfma_f32_16x16x32_bf16 v[42:45], v[158:161], v[192:195], v[42:45]
	v_mfma_f32_16x16x32_bf16 v[38:41], v[166:169], v[192:195], v[38:41]
	v_mfma_f32_16x16x32_bf16 v[26:29], v[158:161], v[204:207], v[26:29]
	v_mfma_f32_16x16x32_bf16 v[22:25], v[166:169], v[204:207], v[22:25]
	v_mfma_f32_16x16x32_bf16 v[10:13], v[158:161], v[212:215], v[10:13]
	v_mfma_f32_16x16x32_bf16 v[6:9], v[166:169], v[212:215], v[6:9]
	v_mfma_f32_16x16x32_bf16 v[58:61], v[162:165], v[188:191], v[58:61]
	v_mfma_f32_16x16x32_bf16 v[54:57], v[170:173], v[188:191], v[54:57]
	v_mfma_f32_16x16x32_bf16 v[42:45], v[162:165], v[200:203], v[42:45]
	v_mfma_f32_16x16x32_bf16 v[38:41], v[170:173], v[200:203], v[38:41]
	v_mfma_f32_16x16x32_bf16 v[26:29], v[162:165], v[208:211], v[26:29]
	v_mfma_f32_16x16x32_bf16 v[22:25], v[170:173], v[208:211], v[22:25]
	v_mfma_f32_16x16x32_bf16 v[10:13], v[162:165], v[216:219], v[10:13]
	v_mfma_f32_16x16x32_bf16 v[6:9], v[170:173], v[216:219], v[6:9]
	s_setprio 0
	s_barrier
	s_add_i32 s90, 0, 0x18000
	s_add_i32 s91, 0, 0x1c000
	v_add_u32_e32 v154, s90, v135
	v_add_u32_e32 v170, s91, v135
	ds_read_b128 v[142:145], v154
	ds_read_b128 v[146:149], v154 offset:1024
	ds_read_b128 v[150:153], v154 offset:2048
	ds_read_b128 v[154:157], v154 offset:3072
	ds_read_b128 v[158:161], v170
	ds_read_b128 v[162:165], v170 offset:1024
	ds_read_b128 v[166:169], v170 offset:2048
	ds_read_b128 v[170:173], v170 offset:3072
	s_add_u32 s30, s30, 0x40000
	s_addc_u32 s31, s31, 0
	s_mov_b32 m0, s60
	v_lshl_add_u64 v[238:239], s[30:31], 0, v[178:179]
	ds_read_b128 v[184:187], v236 offset:32768
	ds_read_b128 v[188:191], v236 offset:33792
	ds_read_b128 v[192:195], v236 offset:34816
	ds_read_b128 v[200:203], v236 offset:35840
	ds_read_b128 v[204:207], v236 offset:36864
	ds_read_b128 v[208:211], v236 offset:37888
	ds_read_b128 v[212:215], v236 offset:38912
	ds_read_b128 v[216:219], v236 offset:39936
	global_load_lds_dwordx4 v[238:239], off
	v_lshl_add_u64 v[238:239], s[30:31], 0, v[136:137]
	s_mov_b32 m0, s72
	s_nop 0
	global_load_lds_dwordx4 v[238:239], off
	s_waitcnt vmcnt(8)
	s_waitcnt lgkmcnt(0)
	s_barrier
	s_setprio 1
	v_mfma_f32_16x16x32_bf16 v[130:133], v[142:145], v[184:187], v[130:133]
	v_mfma_f32_16x16x32_bf16 v[126:129], v[150:153], v[184:187], v[126:129]
	v_mfma_f32_16x16x32_bf16 v[114:117], v[142:145], v[192:195], v[114:117]
	v_mfma_f32_16x16x32_bf16 v[110:113], v[150:153], v[192:195], v[110:113]
	v_mfma_f32_16x16x32_bf16 v[98:101], v[142:145], v[204:207], v[98:101]
	v_mfma_f32_16x16x32_bf16 v[94:97], v[150:153], v[204:207], v[94:97]
	v_mfma_f32_16x16x32_bf16 v[82:85], v[142:145], v[212:215], v[82:85]
	v_mfma_f32_16x16x32_bf16 v[78:81], v[150:153], v[212:215], v[78:81]
	v_mfma_f32_16x16x32_bf16 v[130:133], v[146:149], v[188:191], v[130:133]
	v_mfma_f32_16x16x32_bf16 v[126:129], v[154:157], v[188:191], v[126:129]
	v_mfma_f32_16x16x32_bf16 v[114:117], v[146:149], v[200:203], v[114:117]
	v_mfma_f32_16x16x32_bf16 v[110:113], v[154:157], v[200:203], v[110:113]
	v_mfma_f32_16x16x32_bf16 v[98:101], v[146:149], v[208:211], v[98:101]
	v_mfma_f32_16x16x32_bf16 v[94:97], v[154:157], v[208:211], v[94:97]
	v_mfma_f32_16x16x32_bf16 v[82:85], v[146:149], v[216:219], v[82:85]
	v_mfma_f32_16x16x32_bf16 v[78:81], v[154:157], v[216:219], v[78:81]
	v_mfma_f32_16x16x32_bf16 v[122:125], v[158:161], v[184:187], v[122:125]
	v_mfma_f32_16x16x32_bf16 v[118:121], v[166:169], v[184:187], v[118:121]
	v_mfma_f32_16x16x32_bf16 v[106:109], v[158:161], v[192:195], v[106:109]
	v_mfma_f32_16x16x32_bf16 v[102:105], v[166:169], v[192:195], v[102:105]
	v_mfma_f32_16x16x32_bf16 v[90:93], v[158:161], v[204:207], v[90:93]
	v_mfma_f32_16x16x32_bf16 v[86:89], v[166:169], v[204:207], v[86:89]
	v_mfma_f32_16x16x32_bf16 v[74:77], v[158:161], v[212:215], v[74:77]
	v_mfma_f32_16x16x32_bf16 v[70:73], v[166:169], v[212:215], v[70:73]
	v_mfma_f32_16x16x32_bf16 v[122:125], v[162:165], v[188:191], v[122:125]
	v_mfma_f32_16x16x32_bf16 v[118:121], v[170:173], v[188:191], v[118:121]
	v_mfma_f32_16x16x32_bf16 v[106:109], v[162:165], v[200:203], v[106:109]
	v_mfma_f32_16x16x32_bf16 v[102:105], v[170:173], v[200:203], v[102:105]
	v_mfma_f32_16x16x32_bf16 v[90:93], v[162:165], v[208:211], v[90:93]
	v_mfma_f32_16x16x32_bf16 v[86:89], v[170:173], v[208:211], v[86:89]
	v_mfma_f32_16x16x32_bf16 v[74:77], v[162:165], v[216:219], v[74:77]
	v_mfma_f32_16x16x32_bf16 v[70:73], v[170:173], v[216:219], v[70:73]
	s_setprio 0
	s_barrier
; #define PG8_STAGE(bufoff, gbase, voff) do { _Pragma("unroll") for (int _i = 0; _i < 2; ++_i) \
;         __builtin_amdgcn_global_load_lds((const unsigned*)((const char*)(gbase) + (voff)[_i]), (PG8_LAS unsigned*)(lds + (bufoff) + ldsw + _i * 8192), 16, 0, 0); } while (0)
; #define PG8_LDA(dst, b, h) do { _Pragma("unroll") for (int m = 0; m < 4; ++m) _Pragma("unroll") for (int k = 0; k < 2; ++k) dst[m][k] = *(const PG8_LAS bf16x8*)(lds + PG8_SA(b, h) + aoff + m * 2048 + k * 1024); } while (0)
; #define PG8_MMA(ai, bj, At, Bt) do { __builtin_amdgcn_s_setprio(1); _Pragma("unroll") for (int m = 0; m < 4; ++m) _Pragma("unroll") for (int n = 0; n < 2; ++n) _Pragma("unroll") for (int k = 0; k < 2; ++k) \
;         acc[ai][bj][m][n] = __builtin_amdgcn_mfma_f32_16x16x32_bf16(Bt[n][k], At[m][k], acc[ai][bj][m][n], 0, 0, 0); __builtin_amdgcn_s_setprio(0); } while (0)
; #define PG8_WAIT_V(n) asm volatile("s_waitcnt vmcnt(" #n ")" ::: "memory")
; #define PG8_WAIT_L(n) asm volatile("s_waitcnt lgkmcnt(" #n ")" ::: "memory")
; #define PG8_BAR __builtin_amdgcn_s_barrier()
; #define PG8_SCHED __builtin_amdgcn_sched_barrier(0)
; template <class Epi, class Sched, bool ALIGN_EPI = false, bool SP2 = false>
; __device__ __forceinline__ void gemm_phase(PG8_LAS unsigned char* lds, const Gemm g, const Sched& S, const Epi& E) {
;     ...
;             PG8_LDA(At, 1, 1); PG8_STAGE(PG8_SB(1, 0), b3, voffB); PG8_STAGE(PG8_SB(1, 1), b3 + hstep, voffB); PG8_STAGE(PG8_SA(1, 0), a3, voffA);
;             PG8_WAIT_V(8); PG8_WAIT_L(0); PG8_BAR; PG8_MMA(1, 0, At, B0); PG8_MMA(1, 1, At, B1); PG8_BAR; PG8_SCHED;
	s_add_i32 s30, s90, s39
	v_lshl_add_u64 v[174:175], v[174:175], 0, s[64:65]
	s_mov_b32 m0, s30
	ds_read_b128 v[184:187], v236 offset:49152
	ds_read_b128 v[188:191], v236 offset:50176
	ds_read_b128 v[192:195], v236 offset:51200
	ds_read_b128 v[200:203], v236 offset:52224
	ds_read_b128 v[204:207], v236 offset:53248
	ds_read_b128 v[208:211], v236 offset:54272
	ds_read_b128 v[212:215], v236 offset:55296
	ds_read_b128 v[216:219], v236 offset:56320
	global_load_lds_dwordx4 v[174:175], off
	s_add_i32 m0, s30, 0x2000
	s_add_u32 s26, s26, 0x40080
	v_lshl_add_u64 v[174:175], v[196:197], 0, s[64:65]
	s_addc_u32 s27, s27, 0
	s_add_i32 s30, s91, s39
	global_load_lds_dwordx4 v[174:175], off
	v_lshl_add_u64 v[174:175], s[26:27], 0, v[176:177]
	s_mov_b32 m0, s30
	s_nop 0
	global_load_lds_dwordx4 v[174:175], off
	v_lshl_add_u64 v[174:175], s[26:27], 0, v[2:3]
	s_add_i32 m0, s30, 0x2000
	s_nop 0
	global_load_lds_dwordx4 v[174:175], off
	v_lshl_add_u64 v[174:175], v[228:229], 0, s[64:65]
	s_mov_b32 m0, s73
	s_nop 0
	global_load_lds_dwordx4 v[174:175], off
	v_lshl_add_u64 v[174:175], v[230:231], 0, s[64:65]
	s_mov_b32 m0, s76
	s_nop 0
	global_load_lds_dwordx4 v[174:175], off
	s_waitcnt vmcnt(8)
	s_waitcnt lgkmcnt(0)
	s_barrier
	s_setprio 1
	v_mfma_f32_16x16x32_bf16 v[66:69], v[142:145], v[184:187], v[66:69]
	v_mfma_f32_16x16x32_bf16 v[62:65], v[150:153], v[184:187], v[62:65]
	v_mfma_f32_16x16x32_bf16 v[50:53], v[142:145], v[192:195], v[50:53]
	v_mfma_f32_16x16x32_bf16 v[46:49], v[150:153], v[192:195], v[46:49]
	v_mfma_f32_16x16x32_bf16 v[34:37], v[142:145], v[204:207], v[34:37]
	v_mfma_f32_16x16x32_bf16 v[30:33], v[150:153], v[204:207], v[30:33]
	v_mfma_f32_16x16x32_bf16 v[18:21], v[142:145], v[212:215], v[18:21]
	v_mfma_f32_16x16x32_bf16 v[14:17], v[150:153], v[212:215], v[14:17]
	v_mfma_f32_16x16x32_bf16 v[66:69], v[146:149], v[188:191], v[66:69]
	v_mfma_f32_16x16x32_bf16 v[62:65], v[154:157], v[188:191], v[62:65]
	v_mfma_f32_16x16x32_bf16 v[50:53], v[146:149], v[200:203], v[50:53]
	v_mfma_f32_16x16x32_bf16 v[46:49], v[154:157], v[200:203], v[46:49]
	v_mfma_f32_16x16x32_bf16 v[34:37], v[146:149], v[208:211], v[34:37]
	v_mfma_f32_16x16x32_bf16 v[30:33], v[154:157], v[208:211], v[30:33]
	v_mfma_f32_16x16x32_bf16 v[18:21], v[146:149], v[216:219], v[18:21]
	v_mfma_f32_16x16x32_bf16 v[14:17], v[154:157], v[216:219], v[14:17]
	v_mfma_f32_16x16x32_bf16 v[58:61], v[158:161], v[184:187], v[58:61]
	v_mfma_f32_16x16x32_bf16 v[54:57], v[166:169], v[184:187], v[54:57]
	v_mfma_f32_16x16x32_bf16 v[42:45], v[158:161], v[192:195], v[42:45]
	v_mfma_f32_16x16x32_bf16 v[38:41], v[166:169], v[192:195], v[38:41]
	v_mfma_f32_16x16x32_bf16 v[26:29], v[158:161], v[204:207], v[26:29]
	v_mfma_f32_16x16x32_bf16 v[22:25], v[166:169], v[204:207], v[22:25]
	v_mfma_f32_16x16x32_bf16 v[10:13], v[158:161], v[212:215], v[10:13]
	v_mfma_f32_16x16x32_bf16 v[6:9], v[166:169], v[212:215], v[6:9]
	v_mfma_f32_16x16x32_bf16 v[58:61], v[162:165], v[188:191], v[58:61]
	v_mfma_f32_16x16x32_bf16 v[54:57], v[170:173], v[188:191], v[54:57]
	v_mfma_f32_16x16x32_bf16 v[42:45], v[162:165], v[200:203], v[42:45]
	v_mfma_f32_16x16x32_bf16 v[38:41], v[170:173], v[200:203], v[38:41]
	v_mfma_f32_16x16x32_bf16 v[26:29], v[162:165], v[208:211], v[26:29]
	v_mfma_f32_16x16x32_bf16 v[22:25], v[170:173], v[208:211], v[22:25]
	v_mfma_f32_16x16x32_bf16 v[10:13], v[162:165], v[216:219], v[10:13]
	v_mfma_f32_16x16x32_bf16 v[6:9], v[170:173], v[216:219], v[6:9]
	s_setprio 0
	s_barrier
	s_add_i32 s89, s89, 2
	s_add_u32 s8, s8, 0x100
	s_addc_u32 s9, s9, 0
	s_add_u32 s85, s85, 0x100
	s_addc_u32 s88, s88, 0
	s_cmp_gt_u32 s89, 13
	s_cbranch_scc0 .LBB0_1390
	s_and_b64 vcc, exec, s[12:13]
	s_cbranch_vccz .LBB0_1393
	s_barrier

; #define PG8_STAGE(bufoff, gbase, voff) do { _Pragma("unroll") for (int _i = 0; _i < 2; ++_i) \
;         __builtin_amdgcn_global_load_lds((const unsigned*)((const char*)(gbase) + (voff)[_i]), (PG8_LAS unsigned*)(lds + (bufoff) + ldsw + _i * 8192), 16, 0, 0); } while (0)
; #define PG8_LDA(dst, b, h) do { _Pragma("unroll") for (int m = 0; m < 4; ++m) _Pragma("unroll") for (int k = 0; k < 2; ++k) dst[m][k] = *(const PG8_LAS bf16x8*)(lds + PG8_SA(b, h) + aoff + m * 2048 + k * 1024); } while (0)
; #define PG8_LDB(dst, b, h) do { _Pragma("unroll") for (int n = 0; n < 2; ++n) _Pragma("unroll") for (int k = 0; k < 2; ++k) dst[n][k] = *(const PG8_LAS bf16x8*)(lds + PG8_SB(b, h) + boff + n * 2048 + k * 1024); } while (0)
; #define PG8_MMA(ai, bj, At, Bt) do { __builtin_amdgcn_s_setprio(1); _Pragma("unroll") for (int m = 0; m < 4; ++m) _Pragma("unroll") for (int n = 0; n < 2; ++n) _Pragma("unroll") for (int k = 0; k < 2; ++k) \
;         acc[ai][bj][m][n] = __builtin_amdgcn_mfma_f32_16x16x32_bf16(Bt[n][k], At[m][k], acc[ai][bj][m][n], 0, 0, 0); __builtin_amdgcn_s_setprio(0); } while (0)
; #define PG8_WAIT_V(n) asm volatile("s_waitcnt vmcnt(" #n ")" ::: "memory")
; #define PG8_WAIT_L(n) asm volatile("s_waitcnt lgkmcnt(" #n ")" ::: "memory")
; #define PG8_BAR __builtin_amdgcn_s_barrier()
; #define PG8_SCHED __builtin_amdgcn_sched_barrier(0)
; template <class Epi, class Sched, bool ALIGN_EPI = false, bool SP2 = false>
; __device__ __forceinline__ void gemm_phase(PG8_LAS unsigned char* lds, const Gemm g, const Sched& S, const Epi& E) {
;     ...
;             PG8_LDB(B0, 0, 0); PG8_LDB(B1, 0, 1); PG8_SCHED; PG8_LDA(At, 0, 0); PG8_STAGE(PG8_SA(1, 1), a1 + hstep, voffA);
;             PG8_WAIT_V(8); PG8_WAIT_L(0); PG8_BAR; PG8_MMA(0, 0, At, B0); PG8_MMA(0, 1, At, B1); PG8_BAR; PG8_SCHED;
;             PG8_LDA(At, 0, 1); PG8_STAGE(PG8_SB(0, 0), b2, voffB); PG8_STAGE(PG8_SB(0, 1), b2 + hstep, voffB); PG8_STAGE(PG8_SA(0, 0), a2, voffA);
;             PG8_WAIT_V(8); PG8_WAIT_L(0); PG8_BAR; PG8_MMA(1, 0, At, B0); PG8_MMA(1, 1, At, B1); PG8_BAR; PG8_SCHED;
.LBB0_1506:
	s_add_u32 s22, s8, 0xfff80080
	s_addc_u32 s23, s9, -1
	s_add_i32 s69, 0, 0x10000
	s_cmp_eq_u32 s15, 28
	s_cselect_b32 s81, s39, s23
	s_cselect_b32 s80, vcc_lo, s22
	s_cselect_b32 s77, s31, s14
	s_cselect_b32 s76, vcc_hi, s93
	s_add_i32 s60, 0, 0x14000
	v_add_u32_e32 v78, s69, v135
	v_add_u32_e32 v170, s60, v135
	ds_read_b128 v[66:69], v78
	ds_read_b128 v[70:73], v78 offset:1024
	ds_read_b128 v[74:77], v78 offset:2048
	ds_read_b128 v[78:81], v78 offset:3072
	ds_read_b128 v[158:161], v170
	ds_read_b128 v[162:165], v170 offset:1024
	ds_read_b128 v[166:169], v170 offset:2048
	ds_read_b128 v[170:173], v170 offset:3072
	v_lshl_add_u64 v[212:213], s[8:9], 0, v[200:201]
	s_add_i32 m0, s85, 0xc000
	ds_read_b128 v[174:177], v215
	ds_read_b128 v[178:181], v215 offset:1024
	ds_read_b128 v[182:185], v215 offset:2048
	ds_read_b128 v[186:189], v215 offset:3072
	ds_read_b128 v[190:193], v215 offset:4096
	ds_read_b128 v[194:197], v215 offset:5120
	ds_read_b128 v[204:207], v215 offset:6144
	ds_read_b128 v[208:211], v215 offset:7168
	global_load_lds_dwordx4 v[212:213], off
	v_lshl_add_u64 v[212:213], s[8:9], 0, v[202:203]
	s_add_i32 m0, s85, 0xe000
	s_nop 0
	global_load_lds_dwordx4 v[212:213], off
	s_waitcnt vmcnt(8)
	s_waitcnt lgkmcnt(0)
	s_barrier
	s_setprio 1
	v_mfma_f32_16x16x32_bf16 v[154:157], v[66:69], v[174:177], v[154:157]
	v_mfma_f32_16x16x32_bf16 v[150:153], v[74:77], v[174:177], v[150:153]
	v_mfma_f32_16x16x32_bf16 v[142:145], v[66:69], v[182:185], v[142:145]
	v_mfma_f32_16x16x32_bf16 v[126:129], v[74:77], v[182:185], v[126:129]
	v_mfma_f32_16x16x32_bf16 v[114:117], v[66:69], v[190:193], v[114:117]
	v_mfma_f32_16x16x32_bf16 v[110:113], v[74:77], v[190:193], v[110:113]
	v_mfma_f32_16x16x32_bf16 v[102:105], v[66:69], v[204:207], v[102:105]
	v_mfma_f32_16x16x32_bf16 v[94:97], v[74:77], v[204:207], v[94:97]
	v_mfma_f32_16x16x32_bf16 v[154:157], v[70:73], v[178:181], v[154:157]
	v_mfma_f32_16x16x32_bf16 v[150:153], v[78:81], v[178:181], v[150:153]
	v_mfma_f32_16x16x32_bf16 v[142:145], v[70:73], v[186:189], v[142:145]
	v_mfma_f32_16x16x32_bf16 v[126:129], v[78:81], v[186:189], v[126:129]
	v_mfma_f32_16x16x32_bf16 v[114:117], v[70:73], v[194:197], v[114:117]
	v_mfma_f32_16x16x32_bf16 v[110:113], v[78:81], v[194:197], v[110:113]
	v_mfma_f32_16x16x32_bf16 v[102:105], v[70:73], v[208:211], v[102:105]
	v_mfma_f32_16x16x32_bf16 v[94:97], v[78:81], v[208:211], v[94:97]
	v_mfma_f32_16x16x32_bf16 v[146:149], v[158:161], v[174:177], v[146:149]
	v_mfma_f32_16x16x32_bf16 v[130:133], v[166:169], v[174:177], v[130:133]
	v_mfma_f32_16x16x32_bf16 v[122:125], v[158:161], v[182:185], v[122:125]
	v_mfma_f32_16x16x32_bf16 v[118:121], v[166:169], v[182:185], v[118:121]
	v_mfma_f32_16x16x32_bf16 v[106:109], v[158:161], v[190:193], v[106:109]
	v_mfma_f32_16x16x32_bf16 v[98:101], v[166:169], v[190:193], v[98:101]
	v_mfma_f32_16x16x32_bf16 v[90:93], v[158:161], v[204:207], v[90:93]
	v_mfma_f32_16x16x32_bf16 v[86:89], v[166:169], v[204:207], v[86:89]
	v_mfma_f32_16x16x32_bf16 v[146:149], v[162:165], v[178:181], v[146:149]
	v_mfma_f32_16x16x32_bf16 v[130:133], v[170:173], v[178:181], v[130:133]
	v_mfma_f32_16x16x32_bf16 v[122:125], v[162:165], v[186:189], v[122:125]
	v_mfma_f32_16x16x32_bf16 v[118:121], v[170:173], v[186:189], v[118:121]
	v_mfma_f32_16x16x32_bf16 v[106:109], v[162:165], v[194:197], v[106:109]
	v_mfma_f32_16x16x32_bf16 v[98:101], v[170:173], v[194:197], v[98:101]
	v_mfma_f32_16x16x32_bf16 v[90:93], v[162:165], v[208:211], v[90:93]
	v_mfma_f32_16x16x32_bf16 v[86:89], v[170:173], v[208:211], v[86:89]
	s_setprio 0
	s_barrier
	s_add_i32 s22, s69, s35
	v_lshl_add_u64 v[212:213], s[76:77], 0, v[136:137]
	s_mov_b32 m0, s22
	ds_read_b128 v[174:177], v215 offset:16384
	ds_read_b128 v[178:181], v215 offset:17408
	ds_read_b128 v[182:185], v215 offset:18432
	ds_read_b128 v[186:189], v215 offset:19456
	ds_read_b128 v[190:193], v215 offset:20480
	ds_read_b128 v[194:197], v215 offset:21504
	ds_read_b128 v[204:207], v215 offset:22528
	ds_read_b128 v[208:211], v215 offset:23552
	global_load_lds_dwordx4 v[212:213], off
	s_add_i32 m0, s22, 0x2000
	s_add_u32 s22, s76, 0x80000
	v_lshl_add_u64 v[216:217], s[76:77], 0, v[2:3]
	s_addc_u32 s23, s77, 0
	s_add_i32 s60, s60, s35
	global_load_lds_dwordx4 v[216:217], off
	v_lshl_add_u64 v[218:219], s[22:23], 0, v[136:137]
	s_mov_b32 m0, s60
	v_lshl_add_u64 v[228:229], s[80:81], 0, v[2:3]
	global_load_lds_dwordx4 v[218:219], off
	v_lshl_add_u64 v[218:219], s[22:23], 0, v[2:3]
	s_add_i32 m0, s60, 0x2000
	s_nop 0
	global_load_lds_dwordx4 v[218:219], off
	v_lshl_add_u64 v[218:219], s[80:81], 0, v[136:137]
	s_mov_b32 m0, s85
	s_nop 0
	global_load_lds_dwordx4 v[218:219], off
	s_mov_b32 m0, s88
	s_nop 0
	global_load_lds_dwordx4 v[228:229], off
	s_waitcnt vmcnt(8)
	s_waitcnt lgkmcnt(0)
	s_barrier
; #define PG8_STAGE(bufoff, gbase, voff) do { _Pragma("unroll") for (int _i = 0; _i < 2; ++_i) \
;         __builtin_amdgcn_global_load_lds((const unsigned*)((const char*)(gbase) + (voff)[_i]), (PG8_LAS unsigned*)(lds + (bufoff) + ldsw + _i * 8192), 16, 0, 0); } while (0)
; #define PG8_LDA(dst, b, h) do { _Pragma("unroll") for (int m = 0; m < 4; ++m) _Pragma("unroll") for (int k = 0; k < 2; ++k) dst[m][k] = *(const PG8_LAS bf16x8*)(lds + PG8_SA(b, h) + aoff + m * 2048 + k * 1024); } while (0)
; #define PG8_LDB(dst, b, h) do { _Pragma("unroll") for (int n = 0; n < 2; ++n) _Pragma("unroll") for (int k = 0; k < 2; ++k) dst[n][k] = *(const PG8_LAS bf16x8*)(lds + PG8_SB(b, h) + boff + n * 2048 + k * 1024); } while (0)
; #define PG8_MMA(ai, bj, At, Bt) do { __builtin_amdgcn_s_setprio(1); _Pragma("unroll") for (int m = 0; m < 4; ++m) _Pragma("unroll") for (int n = 0; n < 2; ++n) _Pragma("unroll") for (int k = 0; k < 2; ++k) \
;         acc[ai][bj][m][n] = __builtin_amdgcn_mfma_f32_16x16x32_bf16(Bt[n][k], At[m][k], acc[ai][bj][m][n], 0, 0, 0); __builtin_amdgcn_s_setprio(0); } while (0)
; #define PG8_WAIT_V(n) asm volatile("s_waitcnt vmcnt(" #n ")" ::: "memory")
; #define PG8_WAIT_L(n) asm volatile("s_waitcnt lgkmcnt(" #n ")" ::: "memory")
; #define PG8_BAR __builtin_amdgcn_s_barrier()
; #define PG8_SCHED __builtin_amdgcn_sched_barrier(0)
; template <class Epi, class Sched, bool ALIGN_EPI = false, bool SP2 = false>
; __device__ __forceinline__ void gemm_phase(PG8_LAS unsigned char* lds, const Gemm g, const Sched& S, const Epi& E) {
;     ...
;             PG8_WAIT_V(8); PG8_WAIT_L(0); PG8_BAR; PG8_MMA(1, 0, At, B0); PG8_MMA(1, 1, At, B1); PG8_BAR; PG8_SCHED;
;             PG8_LDB(B0, 1, 0); PG8_LDB(B1, 1, 1); PG8_SCHED; PG8_LDA(At, 1, 0); PG8_STAGE(PG8_SA(0, 1), a2 + hstep, voffA);
;             PG8_WAIT_V(8); PG8_WAIT_L(0); PG8_BAR; PG8_MMA(0, 0, At, B0); PG8_MMA(0, 1, At, B1); PG8_BAR; PG8_SCHED;
	s_setprio 1
	v_mfma_f32_16x16x32_bf16 v[82:85], v[66:69], v[174:177], v[82:85]
	v_mfma_f32_16x16x32_bf16 v[62:65], v[74:77], v[174:177], v[62:65]
	v_mfma_f32_16x16x32_bf16 v[54:57], v[66:69], v[182:185], v[54:57]
	v_mfma_f32_16x16x32_bf16 v[46:49], v[74:77], v[182:185], v[46:49]
	v_mfma_f32_16x16x32_bf16 v[34:37], v[66:69], v[190:193], v[34:37]
	v_mfma_f32_16x16x32_bf16 v[30:33], v[74:77], v[190:193], v[30:33]
	v_mfma_f32_16x16x32_bf16 v[22:25], v[66:69], v[204:207], v[22:25]
	v_mfma_f32_16x16x32_bf16 v[14:17], v[74:77], v[204:207], v[14:17]
	v_mfma_f32_16x16x32_bf16 v[82:85], v[70:73], v[178:181], v[82:85]
	v_mfma_f32_16x16x32_bf16 v[62:65], v[78:81], v[178:181], v[62:65]
	v_mfma_f32_16x16x32_bf16 v[54:57], v[70:73], v[186:189], v[54:57]
	v_mfma_f32_16x16x32_bf16 v[46:49], v[78:81], v[186:189], v[46:49]
	v_mfma_f32_16x16x32_bf16 v[34:37], v[70:73], v[194:197], v[34:37]
	v_mfma_f32_16x16x32_bf16 v[30:33], v[78:81], v[194:197], v[30:33]
	v_mfma_f32_16x16x32_bf16 v[22:25], v[70:73], v[208:211], v[22:25]
	v_mfma_f32_16x16x32_bf16 v[14:17], v[78:81], v[208:211], v[14:17]
	v_mfma_f32_16x16x32_bf16 v[58:61], v[158:161], v[174:177], v[58:61]
	v_mfma_f32_16x16x32_bf16 v[50:53], v[166:169], v[174:177], v[50:53]
	v_mfma_f32_16x16x32_bf16 v[42:45], v[158:161], v[182:185], v[42:45]
	v_mfma_f32_16x16x32_bf16 v[38:41], v[166:169], v[182:185], v[38:41]
	v_mfma_f32_16x16x32_bf16 v[26:29], v[158:161], v[190:193], v[26:29]
	v_mfma_f32_16x16x32_bf16 v[18:21], v[166:169], v[190:193], v[18:21]
	v_mfma_f32_16x16x32_bf16 v[10:13], v[158:161], v[204:207], v[10:13]
	v_mfma_f32_16x16x32_bf16 v[6:9], v[166:169], v[204:207], v[6:9]
	v_mfma_f32_16x16x32_bf16 v[58:61], v[162:165], v[178:181], v[58:61]
	v_mfma_f32_16x16x32_bf16 v[50:53], v[170:173], v[178:181], v[50:53]
	v_mfma_f32_16x16x32_bf16 v[42:45], v[162:165], v[186:189], v[42:45]
	v_mfma_f32_16x16x32_bf16 v[38:41], v[170:173], v[186:189], v[38:41]
	v_mfma_f32_16x16x32_bf16 v[26:29], v[162:165], v[194:197], v[26:29]
	v_mfma_f32_16x16x32_bf16 v[18:21], v[170:173], v[194:197], v[18:21]
	v_mfma_f32_16x16x32_bf16 v[10:13], v[162:165], v[208:211], v[10:13]
	v_mfma_f32_16x16x32_bf16 v[6:9], v[170:173], v[208:211], v[6:9]
	s_setprio 0
	s_barrier
	s_add_i32 s60, 0, 0x18000
	s_add_i32 s69, 0, 0x1c000
	v_add_u32_e32 v78, s60, v135
	v_add_u32_e32 v170, s69, v135
	ds_read_b128 v[66:69], v78
	ds_read_b128 v[70:73], v78 offset:1024
	ds_read_b128 v[74:77], v78 offset:2048
	ds_read_b128 v[78:81], v78 offset:3072
	ds_read_b128 v[158:161], v170
	ds_read_b128 v[162:165], v170 offset:1024
	ds_read_b128 v[166:169], v170 offset:2048
	ds_read_b128 v[170:173], v170 offset:3072
	s_add_u32 s22, s80, 0x80000
	s_addc_u32 s23, s81, 0
	s_mov_b32 m0, s89
	v_lshl_add_u64 v[230:231], s[22:23], 0, v[136:137]
	ds_read_b128 v[174:177], v215 offset:32768
	ds_read_b128 v[178:181], v215 offset:33792
	ds_read_b128 v[182:185], v215 offset:34816
	ds_read_b128 v[186:189], v215 offset:35840
	ds_read_b128 v[190:193], v215 offset:36864
	ds_read_b128 v[194:197], v215 offset:37888
	ds_read_b128 v[204:207], v215 offset:38912
	ds_read_b128 v[208:211], v215 offset:39936
	global_load_lds_dwordx4 v[230:231], off
	v_lshl_add_u64 v[230:231], s[22:23], 0, v[2:3]
	s_mov_b32 m0, s90
	s_nop 0
	global_load_lds_dwordx4 v[230:231], off
	s_waitcnt vmcnt(8)
	s_waitcnt lgkmcnt(0)
	s_barrier
	s_setprio 1
	v_mfma_f32_16x16x32_bf16 v[154:157], v[66:69], v[174:177], v[154:157]
	v_mfma_f32_16x16x32_bf16 v[150:153], v[74:77], v[174:177], v[150:153]
	v_mfma_f32_16x16x32_bf16 v[142:145], v[66:69], v[182:185], v[142:145]
	v_mfma_f32_16x16x32_bf16 v[126:129], v[74:77], v[182:185], v[126:129]
	v_mfma_f32_16x16x32_bf16 v[114:117], v[66:69], v[190:193], v[114:117]
	v_mfma_f32_16x16x32_bf16 v[110:113], v[74:77], v[190:193], v[110:113]
	v_mfma_f32_16x16x32_bf16 v[102:105], v[66:69], v[204:207], v[102:105]
	v_mfma_f32_16x16x32_bf16 v[94:97], v[74:77], v[204:207], v[94:97]
	v_mfma_f32_16x16x32_bf16 v[154:157], v[70:73], v[178:181], v[154:157]
	v_mfma_f32_16x16x32_bf16 v[150:153], v[78:81], v[178:181], v[150:153]
	v_mfma_f32_16x16x32_bf16 v[142:145], v[70:73], v[186:189], v[142:145]
	v_mfma_f32_16x16x32_bf16 v[126:129], v[78:81], v[186:189], v[126:129]
	v_mfma_f32_16x16x32_bf16 v[114:117], v[70:73], v[194:197], v[114:117]
	v_mfma_f32_16x16x32_bf16 v[110:113], v[78:81], v[194:197], v[110:113]
	v_mfma_f32_16x16x32_bf16 v[102:105], v[70:73], v[208:211], v[102:105]
	v_mfma_f32_16x16x32_bf16 v[94:97], v[78:81], v[208:211], v[94:97]
	v_mfma_f32_16x16x32_bf16 v[146:149], v[158:161], v[174:177], v[146:149]
	v_mfma_f32_16x16x32_bf16 v[130:133], v[166:169], v[174:177], v[130:133]
	v_mfma_f32_16x16x32_bf16 v[122:125], v[158:161], v[182:185], v[122:125]
	v_mfma_f32_16x16x32_bf16 v[118:121], v[166:169], v[182:185], v[118:121]
	v_mfma_f32_16x16x32_bf16 v[106:109], v[158:161], v[190:193], v[106:109]
	v_mfma_f32_16x16x32_bf16 v[98:101], v[166:169], v[190:193], v[98:101]
	v_mfma_f32_16x16x32_bf16 v[90:93], v[158:161], v[204:207], v[90:93]
	v_mfma_f32_16x16x32_bf16 v[86:89], v[166:169], v[204:207], v[86:89]
	v_mfma_f32_16x16x32_bf16 v[146:149], v[162:165], v[178:181], v[146:149]
	v_mfma_f32_16x16x32_bf16 v[130:133], v[170:173], v[178:181], v[130:133]
	v_mfma_f32_16x16x32_bf16 v[122:125], v[162:165], v[186:189], v[122:125]
	v_mfma_f32_16x16x32_bf16 v[118:121], v[170:173], v[186:189], v[118:121]
	v_mfma_f32_16x16x32_bf16 v[106:109], v[162:165], v[194:197], v[106:109]
	v_mfma_f32_16x16x32_bf16 v[98:101], v[170:173], v[194:197], v[98:101]
	v_mfma_f32_16x16x32_bf16 v[90:93], v[162:165], v[208:211], v[90:93]
	v_mfma_f32_16x16x32_bf16 v[86:89], v[170:173], v[208:211], v[86:89]
	s_setprio 0
	s_barrier
; #define PG8_STAGE(bufoff, gbase, voff) do { _Pragma("unroll") for (int _i = 0; _i < 2; ++_i) \
;         __builtin_amdgcn_global_load_lds((const unsigned*)((const char*)(gbase) + (voff)[_i]), (PG8_LAS unsigned*)(lds + (bufoff) + ldsw + _i * 8192), 16, 0, 0); } while (0)
; #define PG8_LDA(dst, b, h) do { _Pragma("unroll") for (int m = 0; m < 4; ++m) _Pragma("unroll") for (int k = 0; k < 2; ++k) dst[m][k] = *(const PG8_LAS bf16x8*)(lds + PG8_SA(b, h) + aoff + m * 2048 + k * 1024); } while (0)
; #define PG8_MMA(ai, bj, At, Bt) do { __builtin_amdgcn_s_setprio(1); _Pragma("unroll") for (int m = 0; m < 4; ++m) _Pragma("unroll") for (int n = 0; n < 2; ++n) _Pragma("unroll") for (int k = 0; k < 2; ++k) \
;         acc[ai][bj][m][n] = __builtin_amdgcn_mfma_f32_16x16x32_bf16(Bt[n][k], At[m][k], acc[ai][bj][m][n], 0, 0, 0); __builtin_amdgcn_s_setprio(0); } while (0)
; #define PG8_WAIT_V(n) asm volatile("s_waitcnt vmcnt(" #n ")" ::: "memory")
; #define PG8_WAIT_L(n) asm volatile("s_waitcnt lgkmcnt(" #n ")" ::: "memory")
; #define PG8_BAR __builtin_amdgcn_s_barrier()
; #define PG8_SCHED __builtin_amdgcn_sched_barrier(0)
; template <class Epi, class Sched, bool ALIGN_EPI = false, bool SP2 = false>
; __device__ __forceinline__ void gemm_phase(PG8_LAS unsigned char* lds, const Gemm g, const Sched& S, const Epi& E) {
;     ...
;             PG8_LDA(At, 1, 1); PG8_STAGE(PG8_SB(1, 0), b3, voffB); PG8_STAGE(PG8_SB(1, 1), b3 + hstep, voffB); PG8_STAGE(PG8_SA(1, 0), a3, voffA);
;             PG8_WAIT_V(8); PG8_WAIT_L(0); PG8_BAR; PG8_MMA(1, 0, At, B0); PG8_MMA(1, 1, At, B1); PG8_BAR; PG8_SCHED;
	s_add_i32 s22, s60, s35
	v_lshl_add_u64 v[212:213], v[212:213], 0, s[64:65]
	s_mov_b32 m0, s22
	ds_read_b128 v[174:177], v215 offset:49152
	ds_read_b128 v[178:181], v215 offset:50176
	ds_read_b128 v[182:185], v215 offset:51200
	ds_read_b128 v[186:189], v215 offset:52224
	ds_read_b128 v[190:193], v215 offset:53248
	ds_read_b128 v[194:197], v215 offset:54272
	ds_read_b128 v[204:207], v215 offset:55296
	ds_read_b128 v[208:211], v215 offset:56320
	global_load_lds_dwordx4 v[212:213], off
	s_add_i32 m0, s22, 0x2000
	s_add_u32 s22, s76, 0x80080
	v_lshl_add_u64 v[212:213], v[216:217], 0, s[64:65]
	s_addc_u32 s23, s77, 0
	s_add_i32 s60, s69, s35
	global_load_lds_dwordx4 v[212:213], off
	v_lshl_add_u64 v[212:213], s[22:23], 0, v[136:137]
	s_mov_b32 m0, s60
	s_nop 0
	global_load_lds_dwordx4 v[212:213], off
	v_lshl_add_u64 v[212:213], s[22:23], 0, v[2:3]
	s_add_i32 m0, s60, 0x2000
	s_nop 0
	global_load_lds_dwordx4 v[212:213], off
	v_lshl_add_u64 v[212:213], v[218:219], 0, s[64:65]
	s_mov_b32 m0, s91
	s_nop 0
	global_load_lds_dwordx4 v[212:213], off
	v_lshl_add_u64 v[212:213], v[228:229], 0, s[64:65]
	s_mov_b32 m0, s16
	s_nop 0
	global_load_lds_dwordx4 v[212:213], off
	s_waitcnt vmcnt(8)
	s_waitcnt lgkmcnt(0)
	s_barrier
	s_setprio 1
	v_mfma_f32_16x16x32_bf16 v[82:85], v[66:69], v[174:177], v[82:85]
	v_mfma_f32_16x16x32_bf16 v[62:65], v[74:77], v[174:177], v[62:65]
	v_mfma_f32_16x16x32_bf16 v[54:57], v[66:69], v[182:185], v[54:57]
	v_mfma_f32_16x16x32_bf16 v[46:49], v[74:77], v[182:185], v[46:49]
	v_mfma_f32_16x16x32_bf16 v[34:37], v[66:69], v[190:193], v[34:37]
	v_mfma_f32_16x16x32_bf16 v[30:33], v[74:77], v[190:193], v[30:33]
	v_mfma_f32_16x16x32_bf16 v[22:25], v[66:69], v[204:207], v[22:25]
	v_mfma_f32_16x16x32_bf16 v[14:17], v[74:77], v[204:207], v[14:17]
	v_mfma_f32_16x16x32_bf16 v[82:85], v[70:73], v[178:181], v[82:85]
	v_mfma_f32_16x16x32_bf16 v[62:65], v[78:81], v[178:181], v[62:65]
	v_mfma_f32_16x16x32_bf16 v[54:57], v[70:73], v[186:189], v[54:57]
	v_mfma_f32_16x16x32_bf16 v[46:49], v[78:81], v[186:189], v[46:49]
	v_mfma_f32_16x16x32_bf16 v[34:37], v[70:73], v[194:197], v[34:37]
	v_mfma_f32_16x16x32_bf16 v[30:33], v[78:81], v[194:197], v[30:33]
	v_mfma_f32_16x16x32_bf16 v[22:25], v[70:73], v[208:211], v[22:25]
	v_mfma_f32_16x16x32_bf16 v[14:17], v[78:81], v[208:211], v[14:17]
	v_mfma_f32_16x16x32_bf16 v[58:61], v[158:161], v[174:177], v[58:61]
	v_mfma_f32_16x16x32_bf16 v[50:53], v[166:169], v[174:177], v[50:53]
	v_mfma_f32_16x16x32_bf16 v[42:45], v[158:161], v[182:185], v[42:45]
	v_mfma_f32_16x16x32_bf16 v[38:41], v[166:169], v[182:185], v[38:41]
	v_mfma_f32_16x16x32_bf16 v[26:29], v[158:161], v[190:193], v[26:29]
	v_mfma_f32_16x16x32_bf16 v[18:21], v[166:169], v[190:193], v[18:21]
	v_mfma_f32_16x16x32_bf16 v[10:13], v[158:161], v[204:207], v[10:13]
	v_mfma_f32_16x16x32_bf16 v[6:9], v[166:169], v[204:207], v[6:9]
	v_mfma_f32_16x16x32_bf16 v[58:61], v[162:165], v[178:181], v[58:61]
	v_mfma_f32_16x16x32_bf16 v[50:53], v[170:173], v[178:181], v[50:53]
	v_mfma_f32_16x16x32_bf16 v[42:45], v[162:165], v[186:189], v[42:45]
	v_mfma_f32_16x16x32_bf16 v[38:41], v[170:173], v[186:189], v[38:41]
	v_mfma_f32_16x16x32_bf16 v[26:29], v[162:165], v[194:197], v[26:29]
	v_mfma_f32_16x16x32_bf16 v[18:21], v[170:173], v[194:197], v[18:21]
	v_mfma_f32_16x16x32_bf16 v[10:13], v[162:165], v[208:211], v[10:13]
	v_mfma_f32_16x16x32_bf16 v[6:9], v[170:173], v[208:211], v[6:9]
	s_setprio 0
	s_barrier
	s_add_i32 s15, s15, 2
	s_add_u32 s8, s8, 0x100
	s_addc_u32 s9, s9, 0
	s_add_u32 s93, s93, 0x100
	s_addc_u32 s14, s14, 0
	s_cmp_gt_u32 s15, 29
	s_cbranch_scc0 .LBB0_1506
	v_readlane_b32 s8, v254, 26
	v_readlane_b32 s9, v254, 27
	s_and_b64 vcc, exec, s[8:9]
	s_cbranch_vccz .LBB0_1509
	s_barrier
